# loop-edge edit: NAT attention score/bias chain (64 blocks linked by wave-uniform isP branches) emitted as two straight-line paths
# speedup vs baseline: 1.0055x; 1.0029x over previous
.LBB0_270:
	s_barrier
	ds_write_b128 v126, v[32:35]
	ds_write_b128 v127, v[44:47]
	ds_write_b16 v122, v40 offset:8192
	ds_write_b16_d16_hi v123, v40 offset:8328
	ds_write_b16 v122, v41 offset:8464
	ds_write_b16_d16_hi v123, v41 offset:8600
	ds_write_b16 v122, v42 offset:8736
	ds_write_b16_d16_hi v123, v42 offset:8872
	ds_write_b16 v122, v43 offset:9008
	ds_write_b16_d16_hi v123, v43 offset:9144
	ds_write_b16 v122, v36 offset:9280
	ds_write_b16_d16_hi v123, v36 offset:9416
	ds_write_b16 v122, v37 offset:9552
	ds_write_b16_d16_hi v123, v37 offset:9688
	ds_write_b16 v122, v38 offset:9824
	ds_write_b16_d16_hi v123, v38 offset:9960
	ds_write_b16 v122, v39 offset:10096
	ds_write_b16_d16_hi v123, v39 offset:10232
	s_waitcnt lgkmcnt(0)
	s_barrier
	ds_read_b128 v[32:35], v138
	ds_read_b128 v[36:39], v138 offset:4096
	s_waitcnt lgkmcnt(1)
	v_mfma_f32_32x32x16_bf16 v[48:63], v[32:35], v[64:67], 0
	ds_read_b128 v[146:149], v139
	ds_read_b128 v[150:153], v139 offset:4096
	s_add_i32 s40, s33, s44
	v_cmp_ge_u32_e32 vcc, s40, v115
	v_cmp_lt_u32_e64 s[40:41], s40, v120
	s_and_b64 s[96:97], vcc, s[40:41]
	s_andn2_b64 vcc, exec, s[4:5]
	s_waitcnt lgkmcnt(2)
	v_mfma_f32_32x32x16_bf16 v[32:47], v[36:39], v[64:67], 0
	s_waitcnt lgkmcnt(1)
	v_mfma_f32_32x32x16_bf16 v[48:63], v[146:149], v[68:71], v[48:63]
	s_waitcnt lgkmcnt(0)
	v_mfma_f32_32x32x16_bf16 v[32:47], v[150:153], v[68:71], v[32:47]
	ds_read_b128 v[146:149], v140
	ds_read_b128 v[150:153], v140 offset:4096
	s_waitcnt lgkmcnt(1)
	v_mfma_f32_32x32x16_bf16 v[48:63], v[146:149], v[72:75], v[48:63]
	s_waitcnt lgkmcnt(0)
	v_mfma_f32_32x32x16_bf16 v[32:47], v[150:153], v[72:75], v[32:47]
	ds_read_b128 v[146:149], v141
	ds_read_b128 v[150:153], v141 offset:4096
	s_waitcnt lgkmcnt(1)
	v_mfma_f32_32x32x16_bf16 v[48:63], v[146:149], v[76:79], v[48:63]
	s_waitcnt lgkmcnt(0)
	v_mfma_f32_32x32x16_bf16 v[32:47], v[150:153], v[76:79], v[32:47]
	s_nop 9
	v_mul_f32_e32 v147, 0x3e000000, v48
	v_cndmask_b32_e64 v48, 0, 1, s[4:5]
	v_cmp_ne_u32_e64 s[40:41], 1, v48
	s_cbranch_vccnz .Lnat_np
	s_movk_i32 s4, 0x1d0
	v_subrev_u32_e32 v190, 59, v124
	v_subrev_u32_e32 v191, 57, v124
	v_subrev_u32_e32 v192, 51, v124
	v_subrev_u32_e32 v193, 49, v124
	v_subrev_u32_e32 v194, 43, v124
	v_subrev_u32_e32 v195, 41, v124
	v_subrev_u32_e32 v196, 35, v124
	v_subrev_u32_e32 v197, 33, v124
	v_subrev_u32_e32 v198, 27, v124
	v_subrev_u32_e32 v199, 25, v124
	v_subrev_u32_e32 v200, 19, v124
	v_subrev_u32_e32 v201, 17, v124
	v_subrev_u32_e32 v202, 11, v124
	v_subrev_u32_e32 v203, 9, v124
	v_subrev_u32_e32 v204, 3, v124
	v_subrev_u32_e32 v205, 1, v124
	v_subrev_u32_e32 v206, 58, v124
	v_subrev_u32_e32 v207, 56, v124
	v_subrev_u32_e32 v208, 50, v124
	v_subrev_u32_e32 v209, 48, v124
	v_subrev_u32_e32 v210, 42, v124
	v_subrev_u32_e32 v211, 40, v124
	v_subrev_u32_e32 v212, 34, v124
	v_subrev_u32_e32 v213, 32, v124
	v_subrev_u32_e32 v214, 26, v124
	v_subrev_u32_e32 v215, 24, v124
	v_subrev_u32_e32 v216, 18, v124
	v_subrev_u32_e32 v217, 16, v124
	v_subrev_u32_e32 v218, 10, v124
	v_subrev_u32_e32 v219, 8, v124
	v_subrev_u32_e32 v220, 2, v124
	v_mov_b32_e32 v221, v124
	v_med3_i32 v190, v190, 0, s4
	v_med3_i32 v191, v191, 0, s4
	v_med3_i32 v192, v192, 0, s4
	v_med3_i32 v193, v193, 0, s4
	v_med3_i32 v194, v194, 0, s4
	v_med3_i32 v195, v195, 0, s4
	v_med3_i32 v196, v196, 0, s4
	v_med3_i32 v197, v197, 0, s4
	v_med3_i32 v198, v198, 0, s4
	v_med3_i32 v199, v199, 0, s4
	v_med3_i32 v200, v200, 0, s4
	v_med3_i32 v201, v201, 0, s4
	v_med3_i32 v202, v202, 0, s4
	v_med3_i32 v203, v203, 0, s4
	v_med3_i32 v204, v204, 0, s4
	v_med3_i32 v205, v205, 0, s4
	v_med3_i32 v206, v206, 0, s4
	v_med3_i32 v207, v207, 0, s4
	v_med3_i32 v208, v208, 0, s4
	v_med3_i32 v209, v209, 0, s4
	v_med3_i32 v210, v210, 0, s4
	v_med3_i32 v211, v211, 0, s4
	v_med3_i32 v212, v212, 0, s4
	v_med3_i32 v213, v213, 0, s4
	v_med3_i32 v214, v214, 0, s4
	v_med3_i32 v215, v215, 0, s4
	v_med3_i32 v216, v216, 0, s4
	v_med3_i32 v217, v217, 0, s4
	v_med3_i32 v218, v218, 0, s4
	v_med3_i32 v219, v219, 0, s4
	v_med3_i32 v220, v220, 0, s4
	v_med3_i32 v221, v221, 0, s4
	v_lshl_add_u32 v190, v190, 2, s78
	v_lshl_add_u32 v191, v191, 2, s78
	v_lshl_add_u32 v192, v192, 2, s78
	v_lshl_add_u32 v193, v193, 2, s78
	v_lshl_add_u32 v194, v194, 2, s78
	v_lshl_add_u32 v195, v195, 2, s78
	v_lshl_add_u32 v196, v196, 2, s78
	v_lshl_add_u32 v197, v197, 2, s78
	v_lshl_add_u32 v198, v198, 2, s78
	v_lshl_add_u32 v199, v199, 2, s78
	v_lshl_add_u32 v200, v200, 2, s78
	v_lshl_add_u32 v201, v201, 2, s78
	v_lshl_add_u32 v202, v202, 2, s78
	v_lshl_add_u32 v203, v203, 2, s78
	v_lshl_add_u32 v204, v204, 2, s78
	v_lshl_add_u32 v205, v205, 2, s78
	v_lshl_add_u32 v206, v206, 2, s78
	v_lshl_add_u32 v207, v207, 2, s78
	v_lshl_add_u32 v208, v208, 2, s78
	v_lshl_add_u32 v209, v209, 2, s78
	v_lshl_add_u32 v210, v210, 2, s78
	v_lshl_add_u32 v211, v211, 2, s78
	v_lshl_add_u32 v212, v212, 2, s78
	v_lshl_add_u32 v213, v213, 2, s78
	v_lshl_add_u32 v214, v214, 2, s78
	v_lshl_add_u32 v215, v215, 2, s78
	v_lshl_add_u32 v216, v216, 2, s78
	v_lshl_add_u32 v217, v217, 2, s78
	v_lshl_add_u32 v218, v218, 2, s78
	v_lshl_add_u32 v219, v219, 2, s78
	v_lshl_add_u32 v220, v220, 2, s78
	v_lshl_add_u32 v221, v221, 2, s78
	ds_read_b32 v190, v190 offset:16896
	ds_read_b32 v191, v191 offset:16896
	ds_read_b32 v192, v192 offset:16896
	ds_read_b32 v193, v193 offset:16896
	ds_read_b32 v194, v194 offset:16896
	ds_read_b32 v195, v195 offset:16896
	ds_read_b32 v196, v196 offset:16896
	ds_read_b32 v197, v197 offset:16896
	ds_read_b32 v198, v198 offset:16896
	ds_read_b32 v199, v199 offset:16896
	ds_read_b32 v200, v200 offset:16896
	ds_read_b32 v201, v201 offset:16896
	ds_read_b32 v202, v202 offset:16896
	ds_read_b32 v203, v203 offset:16896
	ds_read_b32 v204, v204 offset:16896
	ds_read_b32 v205, v205 offset:16896
	ds_read_b32 v206, v206 offset:16896
	ds_read_b32 v207, v207 offset:16896
	ds_read_b32 v208, v208 offset:16896
	ds_read_b32 v209, v209 offset:16896
	ds_read_b32 v210, v210 offset:16896
	ds_read_b32 v211, v211 offset:16896
	ds_read_b32 v212, v212 offset:16896
	ds_read_b32 v213, v213 offset:16896
	ds_read_b32 v214, v214 offset:16896
	ds_read_b32 v215, v215 offset:16896
	ds_read_b32 v216, v216 offset:16896
	ds_read_b32 v217, v217 offset:16896
	ds_read_b32 v218, v218 offset:16896
	ds_read_b32 v219, v219 offset:16896
	ds_read_b32 v220, v220 offset:16896
	ds_read_b32 v221, v221 offset:16896
	s_waitcnt lgkmcnt(0)
	s_and_b64 vcc, s[96:97], s[64:65]
	v_add_f32_e32 v48, v147, v190
	v_cndmask_b32_e32 v147, v169, v48, vcc
	v_mul_f32_e32 v146, 0x3e000000, v49
	s_and_b64 vcc, s[96:97], s[66:67]
	v_add_f32_e32 v48, v146, v206
	v_cndmask_b32_e32 v146, v169, v48, vcc
	v_mul_f32_e32 v119, 0x3e000000, v50
	s_and_b64 vcc, s[96:97], s[68:69]
	v_add_f32_e32 v48, v119, v191
	v_cndmask_b32_e32 v119, v169, v48, vcc
	v_mul_f32_e32 v145, 0x3e000000, v51
	s_and_b64 vcc, s[96:97], s[70:71]
	v_add_f32_e32 v48, v145, v207
	v_cndmask_b32_e32 v145, v169, v48, vcc
	v_mul_f32_e32 v51, 0x3e000000, v52
	s_and_b64 vcc, s[96:97], s[72:73]
	v_add_f32_e32 v48, v51, v192
	v_cndmask_b32_e32 v51, v169, v48, vcc
	v_mul_f32_e32 v52, 0x3e000000, v53
	s_and_b64 vcc, s[96:97], s[74:75]
	v_add_f32_e32 v48, v52, v208
	v_cndmask_b32_e32 v52, v169, v48, vcc
	v_mul_f32_e32 v48, 0x3e000000, v54
	v_readlane_b32 s4, v254, 45
	v_readlane_b32 s5, v254, 46
	s_and_b64 vcc, s[96:97], s[4:5]
	v_add_f32_e32 v48, v48, v193
	v_cndmask_b32_e32 v48, v169, v48, vcc
	v_mul_f32_e32 v50, 0x3e000000, v55
	v_readlane_b32 s4, v254, 47
	v_readlane_b32 s5, v254, 48
	s_and_b64 vcc, s[96:97], s[4:5]
	v_add_f32_e32 v49, v50, v209
	v_cndmask_b32_e32 v50, v169, v49, vcc
	v_mul_f32_e32 v49, 0x3e000000, v56
	v_readlane_b32 s4, v254, 49
	v_readlane_b32 s5, v254, 50
	v_readlane_b32 vcc_lo, v254, 51
	s_and_b64 s[4:5], s[96:97], s[4:5]
	v_readlane_b32 vcc_hi, v254, 52
	s_and_b64 vcc, s[4:5], vcc
	v_add_f32_e32 v49, v49, v194
	v_cndmask_b32_e32 v49, v169, v49, vcc
	v_mul_f32_e32 v53, 0x3e000000, v57
	v_readlane_b32 s4, v254, 53
	v_readlane_b32 s5, v254, 54
	v_readlane_b32 vcc_lo, v254, 55
	s_and_b64 s[4:5], s[96:97], s[4:5]
	v_readlane_b32 vcc_hi, v254, 56
	s_and_b64 vcc, s[4:5], vcc
	v_add_f32_e32 v53, v53, v210
	v_cndmask_b32_e32 v53, v169, v53, vcc
	v_mul_f32_e32 v54, 0x3e000000, v58
	v_readlane_b32 s4, v254, 57
	v_readlane_b32 s5, v254, 58
	v_readlane_b32 vcc_lo, v255, 26
	s_and_b64 s[4:5], s[96:97], s[4:5]
	v_readlane_b32 vcc_hi, v255, 27
	s_and_b64 vcc, s[4:5], vcc
	v_add_f32_e32 v54, v54, v195
	v_cndmask_b32_e32 v54, v169, v54, vcc
	v_mul_f32_e32 v55, 0x3e000000, v59
	v_readlane_b32 s4, v255, 28
	v_readlane_b32 s5, v255, 29
	v_readlane_b32 vcc_lo, v255, 30
	s_and_b64 s[4:5], s[96:97], s[4:5]
	v_readlane_b32 vcc_hi, v255, 31
	s_and_b64 vcc, s[4:5], vcc
	v_add_f32_e32 v55, v55, v211
	v_cndmask_b32_e32 v55, v169, v55, vcc
	v_mul_f32_e32 v56, 0x3e000000, v60
	v_readlane_b32 s4, v255, 32
	v_readlane_b32 s5, v255, 33
	v_readlane_b32 vcc_lo, v255, 34
	s_and_b64 s[4:5], s[96:97], s[4:5]
	v_readlane_b32 vcc_hi, v255, 35
	s_and_b64 vcc, s[4:5], vcc
	v_add_f32_e32 v56, v56, v196
	v_cndmask_b32_e32 v56, v169, v56, vcc
	v_mul_f32_e32 v57, 0x3e000000, v61
	v_readlane_b32 s4, v255, 36
	v_readlane_b32 s5, v255, 37
	v_readlane_b32 vcc_lo, v255, 38
	s_and_b64 s[4:5], s[96:97], s[4:5]
	v_readlane_b32 vcc_hi, v255, 39
	s_and_b64 vcc, s[4:5], vcc
	v_add_f32_e32 v57, v57, v212
	v_cndmask_b32_e32 v57, v169, v57, vcc
	v_mul_f32_e32 v58, 0x3e000000, v62
	v_readlane_b32 s4, v255, 40
	v_readlane_b32 s5, v255, 41
	v_readlane_b32 vcc_lo, v255, 42
	s_and_b64 s[4:5], s[96:97], s[4:5]
	v_readlane_b32 vcc_hi, v255, 43
	s_and_b64 vcc, s[4:5], vcc
	v_add_f32_e32 v58, v58, v197
	v_cndmask_b32_e32 v58, v169, v58, vcc
	v_mul_f32_e32 v59, 0x3e000000, v63
	v_readlane_b32 s4, v255, 44
	v_readlane_b32 s5, v255, 45
	v_readlane_b32 vcc_lo, v255, 46
	s_and_b64 s[4:5], s[96:97], s[4:5]
	v_readlane_b32 vcc_hi, v255, 47
	s_and_b64 vcc, s[4:5], vcc
	v_add_f32_e32 v59, v59, v213
	v_cndmask_b32_e32 v59, v169, v59, vcc
	v_mul_f32_e32 v60, 0x3e000000, v32
	v_readlane_b32 s4, v255, 48
	v_readlane_b32 s5, v255, 49
	v_readlane_b32 vcc_lo, v255, 50
	s_and_b64 s[4:5], s[96:97], s[4:5]
	v_readlane_b32 vcc_hi, v255, 51
	s_and_b64 vcc, s[4:5], vcc
	v_add_f32_e32 v32, v60, v198
	v_cndmask_b32_e32 v60, v169, v32, vcc
	v_mul_f32_e32 v61, 0x3e000000, v33
	v_readlane_b32 s4, v255, 52
	v_readlane_b32 s5, v255, 53
	v_readlane_b32 vcc_lo, v255, 54
	s_and_b64 s[4:5], s[96:97], s[4:5]
	v_readlane_b32 vcc_hi, v255, 55
	s_and_b64 vcc, s[4:5], vcc
	v_add_f32_e32 v32, v61, v214
	v_cndmask_b32_e32 v61, v169, v32, vcc
	v_mul_f32_e32 v62, 0x3e000000, v34
	v_readlane_b32 s4, v255, 56
	v_readlane_b32 s5, v255, 57
	v_readlane_b32 vcc_lo, v255, 58
	s_and_b64 s[4:5], s[96:97], s[4:5]
	v_readlane_b32 vcc_hi, v255, 59
	s_and_b64 vcc, s[4:5], vcc
	v_add_f32_e32 v32, v62, v199
	v_cndmask_b32_e32 v62, v169, v32, vcc
	v_mul_f32_e32 v150, 0x3e000000, v35
	v_readlane_b32 s4, v255, 60
	v_readlane_b32 s5, v255, 61
	v_readlane_b32 vcc_lo, v255, 62
	s_and_b64 s[4:5], s[96:97], s[4:5]
	v_readlane_b32 vcc_hi, v255, 63
	s_and_b64 vcc, s[4:5], vcc
	v_add_f32_e32 v32, v150, v215
	v_cndmask_b32_e32 v150, v169, v32, vcc
	v_mul_f32_e32 v151, 0x3e000000, v36
	s_and_b64 s[4:5], s[96:97], s[6:7]
	s_and_b64 vcc, s[4:5], s[8:9]
	v_add_f32_e32 v32, v151, v200
	v_cndmask_b32_e32 v151, v169, v32, vcc
	v_mul_f32_e32 v153, 0x3e000000, v37
	s_and_b64 s[4:5], s[96:97], s[10:11]
	s_and_b64 vcc, s[4:5], s[12:13]
	v_add_f32_e32 v32, v153, v216
	v_cndmask_b32_e32 v153, v169, v32, vcc
	v_mul_f32_e32 v149, 0x3e000000, v38
	s_and_b64 s[4:5], s[96:97], s[14:15]
	s_and_b64 vcc, s[4:5], s[16:17]
	v_add_f32_e32 v32, v149, v201
	v_cndmask_b32_e32 v149, v169, v32, vcc
	v_mul_f32_e32 v152, 0x3e000000, v39
	s_and_b64 s[4:5], s[96:97], s[18:19]
	s_and_b64 vcc, s[4:5], s[20:21]
	v_add_f32_e32 v32, v152, v217
	v_cndmask_b32_e32 v152, v169, v32, vcc
	v_mul_f32_e32 v63, 0x3e000000, v40
	s_and_b64 vcc, s[96:97], s[22:23]
	v_add_f32_e32 v32, v63, v202
	v_cndmask_b32_e32 v63, v169, v32, vcc
	v_mul_f32_e32 v148, 0x3e000000, v41
	s_and_b64 vcc, s[96:97], s[24:25]
	v_add_f32_e32 v32, v148, v218
	v_cndmask_b32_e32 v148, v169, v32, vcc
	v_mul_f32_e32 v41, 0x3e000000, v42
	s_and_b64 vcc, s[96:97], s[26:27]
	v_add_f32_e32 v32, v41, v203
	v_cndmask_b32_e32 v41, v169, v32, vcc
	v_mul_f32_e32 v42, 0x3e000000, v43
	s_and_b64 vcc, s[96:97], s[28:29]
	v_add_f32_e32 v32, v42, v219
	v_cndmask_b32_e32 v42, v169, v32, vcc
	v_mul_f32_e32 v39, 0x3e000000, v44
	s_and_b64 vcc, s[96:97], s[30:31]
	v_add_f32_e32 v32, v39, v204
	v_cndmask_b32_e32 v39, v169, v32, vcc
	v_mul_f32_e32 v45, 0x3e000000, v45
	s_and_b64 vcc, s[96:97], s[34:35]
	v_add_f32_e32 v32, v45, v220
	v_cndmask_b32_e32 v45, v169, v32, vcc
	v_mul_f32_e32 v46, 0x3e000000, v46
	s_and_b64 vcc, s[96:97], s[0:1]
	v_add_f32_e32 v32, v46, v205
	v_cndmask_b32_e32 v46, v169, v32, vcc
	v_mul_f32_e32 v154, 0x3e000000, v47
	s_and_b64 vcc, s[96:97], s[38:39]
	v_add_f32_e32 v32, v154, v221
	v_cndmask_b32_e32 v154, v169, v32, vcc
	s_branch .LBB0_334
.Lnat_np:
	v_mul_f32_e32 v146, 0x3e000000, v49
	v_mul_f32_e32 v119, 0x3e000000, v50
	v_mul_f32_e32 v145, 0x3e000000, v51
	v_mul_f32_e32 v51, 0x3e000000, v52
	v_mul_f32_e32 v52, 0x3e000000, v53
	v_mul_f32_e32 v48, 0x3e000000, v54
	v_mul_f32_e32 v50, 0x3e000000, v55
	v_mul_f32_e32 v49, 0x3e000000, v56
	v_mul_f32_e32 v53, 0x3e000000, v57
	v_mul_f32_e32 v54, 0x3e000000, v58
	v_mul_f32_e32 v55, 0x3e000000, v59
	v_mul_f32_e32 v56, 0x3e000000, v60
	v_mul_f32_e32 v57, 0x3e000000, v61
	v_mul_f32_e32 v58, 0x3e000000, v62
	v_mul_f32_e32 v59, 0x3e000000, v63
	v_mul_f32_e32 v60, 0x3e000000, v32
	v_mul_f32_e32 v61, 0x3e000000, v33
	v_mul_f32_e32 v62, 0x3e000000, v34
	v_mul_f32_e32 v150, 0x3e000000, v35
	v_mul_f32_e32 v151, 0x3e000000, v36
	v_mul_f32_e32 v153, 0x3e000000, v37
	v_mul_f32_e32 v149, 0x3e000000, v38
	v_mul_f32_e32 v152, 0x3e000000, v39
	v_mul_f32_e32 v63, 0x3e000000, v40
	v_mul_f32_e32 v148, 0x3e000000, v41
	v_mul_f32_e32 v41, 0x3e000000, v42
	v_mul_f32_e32 v42, 0x3e000000, v43
	v_mul_f32_e32 v39, 0x3e000000, v44
	v_mul_f32_e32 v45, 0x3e000000, v45
	v_mul_f32_e32 v46, 0x3e000000, v46
	v_mul_f32_e32 v154, 0x3e000000, v47
